# last barrier: one idle wave touches the final-norm gain vector (first read only at the very end of P9) so that read no longer comes from cold HBM
# speedup vs baseline: 1.0029x; 1.0010x over previous
; #define LAS __attribute__((address_space(3)))
; #define GSYNC() xcd_barrier(xb)
;     __device__ __forceinline__ void operator()(f32x4 (&acc)[2][2][4][2], const Unit& u, int wr, int wc, int fr, int fq) const {
;     ...
;         for (int bj = 0; bj < 2; ++bj) { gv[bj][0] = *(const f32x4*)(gf + col0 + bj * HALF); gv[bj][1] = *(const f32x4*)(gf + col0 + bj * HALF + 4); }
; __global__ void __launch_bounds__(512, 2) fwd_megakernel(Params p) {
;     ...
;     GSYNC();
;     { pg8::Gemm g{XB, (const bf16*)(ws + WS_WGU2), S, 2 * DFF, DM}; pg8::StaticOrder so; so.init(S, 2 * DFF, G, (int)blockIdx.x);
;       const int pm0 = fill_rtab(so, SS2, rtab); pg8::EpiSwiGLU E{HB, DFF, SS2, rtab, pm0}; pg8::gemm_phase<pg8::EpiSwiGLU, pg8::StaticOrder, true, true>(ldsl, g, so, E); }
;     { int sgw, sng; if (slack_rank((S / 256) * (2 * DFF / 256), G, sgw, sng)) cvt_down(p, 1, (LAS float*)(ldsl + (threadIdx.x >> 6) * 8448), threadIdx.x & 63, sgw, sng); }
;     GSYNC();
;     { pg8::Gemm g{HB, (const bf16*)(ws + WS_WD2), S, DM, DFF}; pg8::StaticOrder so; so.init(S, DM, G, (int)blockIdx.x);
;       pg8::EpiFinal E{XB, p.out, SS3, (unsigned*)(ws + WS_PCNT), p.nf, 0.5f}; pg8::gemm_phase<pg8::EpiFinal, pg8::StaticOrder, true, true>(ldsl, g, so, E); }
.Leinv_skip_8:
	v_readfirstlane_b32 s2, v152
	s_cmp_lg_u32 s2, 192
	s_cbranch_scc1 .Lnfwarm_skip
	v_and_b32_e32 v0, 63, v152
	v_lshlrev_b32_e32 v0, 4, v0
	v_mov_b32_e32 v1, 0
	v_lshl_add_u64 v[0:1], s[68:69], 0, v[0:1]
	s_mov_b64 s[2:3], 0x80
	s_mov_b32 s8, 0
	s_mov_b32 m0, 0x20010
	s_mov_b64 exec, 0xff
.Lnfwarm_loop:
	global_load_lds_dwordx4 v[0:1], off
	v_lshl_add_u64 v[0:1], v[0:1], 0, s[2:3]
	s_add_u32 s8, s8, 0x80
	s_cmp_lt_u32 s8, 0x1000
	s_cbranch_scc1 .Lnfwarm_loop
	s_mov_b64 exec, -1
